# merge GEMM stagger doubled: XCDs 4-7 start ~20us later (six s_sleep 127) instead of ~10us; otherwise v20
# speedup vs baseline: 1.0038x; 1.0038x over previous
.Lstg7_loop:
	s_sleep 127
	s_sleep 127
	s_sleep 127
	s_sleep 127
	s_sleep 127
	s_sleep 127
	s_sub_u32 s99, s99, 1
	s_cmp_lg_u32 s99, 0
	s_cbranch_scc1 .Lstg7_loop
